# instruction selection (guide 7.5): v_pk_fma_f32 split into scalar v_fma/v_fmac in the DSA score steps
# speedup vs baseline: 1.0058x; 1.0058x over previous
; DI f32x16 mfma32(bf16x8 a, bf16x8 b, f32x16 c) { return __builtin_amdgcn_mfma_f32_32x32x16_bf16(a, b, c, 0, 0, 0); }
; DI u32 mono_key(float f) { u32 u = __float_as_uint(f); return (u & 0x80000000u) ? ~u : (u | 0x80000000u); }
; DI void dsa_item(const Params& p, int l, int tile32, int b, char* smem) {
;     ...
;       for (int t = 0; t < 4; ++t) {
;         const int key = (g * 4 + t) * 32 + c31;
;         f32x16 acc;
; #pragma unroll
;         for (int j = 0; j < 16; ++j) acc[j] = 0.f;
; #pragma unroll
;         for (int s = 0; s < 4; ++s) acc = mfma32(qa[s], kc[t][s], acc);
;         f32x2 ss2 = f32x2{0.f, 0.f};
; #pragma unroll
;         for (int hq = 0; hq < 8; ++hq) {
;           const f32x2 rr = f32x2{__builtin_amdgcn_fmed3f(acc[2 * hq], 0.f, 3.0e38f), __builtin_amdgcn_fmed3f(acc[2 * hq + 1], 0.f, 3.0e38f)};
;           ss2 = __builtin_elementwise_fma(wq2[hq], rr, ss2);
;         }
;         const float s0 = ss2.x, s1 = ss2.y;
;         const u32 k0 = mono_key(s0), k1 = mono_key(s1);
;         const bool c0 = (key <= qpos0) && (k0 > tauA), c1 = (key <= qpos0 + 1) && (k1 > tauB);
;         const u64 m0 = __ballot(c0), m1 = __ballot(c1);
;         if (m0 | m1) {
;           const u32 h0 = hh ? (u32)(m0 >> 32) : (u32)m0, h1 = hh ? (u32)(m1 >> 32) : (u32)m1;
;           const int pA = (hh ? cnt2 : cnt0) + __popc(h0 & lmask), pB = (hh ? cnt3 : cnt1) + __popc(h1 & lmask);
;           if (c0) { ckey[(2 * hh) * DCAP + pA] = k0; cidx[(2 * hh) * DCAP + pA] = (u16)key; }
;           if (c1) { ckey[(2 * hh + 1) * DCAP + pB] = k1; cidx[(2 * hh + 1) * DCAP + pB] = (u16)key; }
;           cnt0 += __popc((u32)m0); cnt2 += __popc((u32)(m0 >> 32));
.LBB0_499:
	s_or_b64 exec, exec, s[2:3]
	v_mfma_f32_32x32x16_bf16 v[2:17], v[18:21], v[2:5], 0
	v_cndmask_b32_e32 v0, v223, v224, vcc
	v_mfma_f32_32x32x16_bf16 v[2:17], v[22:25], v[98:101], v[2:17]
	v_mfma_f32_32x32x16_bf16 v[2:17], v[26:29], v[94:97], v[2:17]
	v_lshl_or_b32 v95, s54, 7, v192
	v_cndmask_b32_e32 v94, v221, v222, vcc
	v_cmp_le_i32_e64 s[0:1], v95, v217
	v_cmp_le_i32_e64 s[2:3], v95, v219
	v_mfma_f32_32x32x16_bf16 v[2:17], v[30:33], v[90:93], v[2:17]
	s_nop 11
	v_med3_f32 v2, v2, 0, v204
	v_med3_f32 v3, v3, 0, v204
	v_med3_f32 v4, v4, 0, v204
	v_med3_f32 v5, v5, 0, v204
	v_fma_f32 v2, v178, v2, 0
	v_fma_f32 v3, v179, v3, 0
	v_med3_f32 v6, v6, 0, v204
	v_med3_f32 v7, v7, 0, v204
	v_fmac_f32_e32 v2, v38, v4
	v_fmac_f32_e32 v3, v39, v5
	v_med3_f32 v8, v8, 0, v204
	v_med3_f32 v9, v9, 0, v204
	v_fmac_f32_e32 v2, v180, v6
	v_fmac_f32_e32 v3, v181, v7
	v_med3_f32 v10, v10, 0, v204
	v_med3_f32 v11, v11, 0, v204
	v_fmac_f32_e32 v2, v40, v8
	v_fmac_f32_e32 v3, v41, v9
	v_med3_f32 v12, v12, 0, v204
	v_med3_f32 v13, v13, 0, v204
	v_fmac_f32_e32 v2, v182, v10
	v_fmac_f32_e32 v3, v183, v11
	v_med3_f32 v14, v14, 0, v204
	v_med3_f32 v15, v15, 0, v204
	v_fmac_f32_e32 v2, v34, v12
	v_fmac_f32_e32 v3, v35, v13
	v_med3_f32 v16, v16, 0, v204
	v_med3_f32 v17, v17, 0, v204
	v_fmac_f32_e32 v2, v184, v14
	v_fmac_f32_e32 v3, v185, v15
	s_nop 0
	v_fma_f32 v4, v36, v16, v2
	v_fma_f32 v5, v37, v17, v3
	s_nop 0
	v_not_b32_e32 v2, v4
	v_or_b32_e32 v3, 0x80000000, v4
	v_cmp_gt_i32_e64 s[4:5], 0, v4
	v_not_b32_e32 v6, v5
	v_or_b32_e32 v7, 0x80000000, v5
	v_cndmask_b32_e64 v3, v3, v2, s[4:5]
	v_cmp_gt_i32_e64 s[4:5], 0, v5
	s_nop 1
	v_cndmask_b32_e64 v2, v7, v6, s[4:5]
	v_cmp_gt_u32_e64 s[4:5], v3, v0
	v_cmp_gt_u32_e64 s[6:7], v2, v94
	s_and_b64 s[10:11], s[0:1], s[4:5]
	s_and_b64 s[4:5], s[2:3], s[6:7]
	s_and_b64 s[0:1], s[10:11], exec
	s_and_b64 s[2:3], s[4:5], exec
	s_or_b64 s[6:7], s[2:3], s[0:1]
	s_cmp_eq_u64 s[6:7], 0
	s_cbranch_scc1 .LBB0_505
	s_and_saveexec_b64 s[6:7], s[10:11]
	s_cbranch_execz .LBB0_502
	v_mov_b32_e32 v4, s1
	v_mov_b32_e32 v5, s0
	v_cndmask_b32_e32 v4, v4, v5, vcc
	v_and_b32_e32 v4, v4, v218
	v_bcnt_u32_b32 v4, v4, 0
	v_cndmask_b32_e32 v5, v187, v173, vcc
	v_add3_u32 v4, v5, v214, v4
	v_lshl_add_u32 v5, v4, 2, v190
	ds_write_b32 v5, v3
	v_lshlrev_b32_e32 v3, 1, v4
	v_sub_u32_e32 v3, v5, v3
	ds_write_b16 v3, v95 offset:10240

; DI f32x16 mfma32(bf16x8 a, bf16x8 b, f32x16 c) { return __builtin_amdgcn_mfma_f32_32x32x16_bf16(a, b, c, 0, 0, 0); }
; DI u32 mono_key(float f) { u32 u = __float_as_uint(f); return (u & 0x80000000u) ? ~u : (u | 0x80000000u); }
; DI void dsa_item(const Params& p, int l, int tile32, int b, char* smem) {
;     ...
;       for (int t = 0; t < 4; ++t) {
;         const int key = (g * 4 + t) * 32 + c31;
;         f32x16 acc;
; #pragma unroll
;         for (int j = 0; j < 16; ++j) acc[j] = 0.f;
; #pragma unroll
;         for (int s = 0; s < 4; ++s) acc = mfma32(qa[s], kc[t][s], acc);
;         f32x2 ss2 = f32x2{0.f, 0.f};
; #pragma unroll
;         for (int hq = 0; hq < 8; ++hq) {
;           const f32x2 rr = f32x2{__builtin_amdgcn_fmed3f(acc[2 * hq], 0.f, 3.0e38f), __builtin_amdgcn_fmed3f(acc[2 * hq + 1], 0.f, 3.0e38f)};
;           ss2 = __builtin_elementwise_fma(wq2[hq], rr, ss2);
;         }
;         const float s0 = ss2.x, s1 = ss2.y;
;         const u32 k0 = mono_key(s0), k1 = mono_key(s1);
;         const bool c0 = (key <= qpos0) && (k0 > tauA), c1 = (key <= qpos0 + 1) && (k1 > tauB);
;         const u64 m0 = __ballot(c0), m1 = __ballot(c1);
;         if (m0 | m1) {
;           const u32 h0 = hh ? (u32)(m0 >> 32) : (u32)m0, h1 = hh ? (u32)(m1 >> 32) : (u32)m1;
;           const int pA = (hh ? cnt2 : cnt0) + __popc(h0 & lmask), pB = (hh ? cnt3 : cnt1) + __popc(h1 & lmask);
;           if (c0) { ckey[(2 * hh) * DCAP + pA] = k0; cidx[(2 * hh) * DCAP + pA] = (u16)key; }
;           if (c1) { ckey[(2 * hh + 1) * DCAP + pB] = k1; cidx[(2 * hh + 1) * DCAP + pB] = (u16)key; }
;           cnt0 += __popc((u32)m0); cnt2 += __popc((u32)(m0 >> 32));
.LBB0_505:
	v_mfma_f32_32x32x16_bf16 v[2:17], v[18:21], v[86:89], 0
	v_mfma_f32_32x32x16_bf16 v[2:17], v[22:25], v[82:85], v[2:17]
	v_mfma_f32_32x32x16_bf16 v[2:17], v[26:29], v[78:81], v[2:17]
	v_or_b32_e32 v78, 32, v95
	v_cmp_le_i32_e64 s[0:1], v78, v217
	v_cmp_le_i32_e64 s[2:3], v78, v219
	v_mfma_f32_32x32x16_bf16 v[2:17], v[30:33], v[74:77], v[2:17]
	s_nop 11
	v_med3_f32 v2, v2, 0, v204
	v_med3_f32 v3, v3, 0, v204
	v_med3_f32 v4, v4, 0, v204
	v_med3_f32 v5, v5, 0, v204
	v_fma_f32 v2, v178, v2, 0
	v_fma_f32 v3, v179, v3, 0
	v_med3_f32 v6, v6, 0, v204
	v_med3_f32 v7, v7, 0, v204
	v_fmac_f32_e32 v2, v38, v4
	v_fmac_f32_e32 v3, v39, v5
	v_med3_f32 v8, v8, 0, v204
	v_med3_f32 v9, v9, 0, v204
	v_fmac_f32_e32 v2, v180, v6
	v_fmac_f32_e32 v3, v181, v7
	v_med3_f32 v10, v10, 0, v204
	v_med3_f32 v11, v11, 0, v204
	v_fmac_f32_e32 v2, v40, v8
	v_fmac_f32_e32 v3, v41, v9
	v_med3_f32 v12, v12, 0, v204
	v_med3_f32 v13, v13, 0, v204
	v_fmac_f32_e32 v2, v182, v10
	v_fmac_f32_e32 v3, v183, v11
	v_med3_f32 v14, v14, 0, v204
	v_med3_f32 v15, v15, 0, v204
	v_fmac_f32_e32 v2, v34, v12
	v_fmac_f32_e32 v3, v35, v13
	v_med3_f32 v16, v16, 0, v204
	v_med3_f32 v17, v17, 0, v204
	v_fmac_f32_e32 v2, v184, v14
	v_fmac_f32_e32 v3, v185, v15
	s_nop 0
	v_fma_f32 v4, v36, v16, v2
	v_fma_f32 v5, v37, v17, v3
	s_nop 0
	v_not_b32_e32 v2, v4
	v_or_b32_e32 v3, 0x80000000, v4
	v_cmp_gt_i32_e64 s[4:5], 0, v4
	v_not_b32_e32 v6, v5
	v_or_b32_e32 v7, 0x80000000, v5
	v_cndmask_b32_e64 v3, v3, v2, s[4:5]
	v_cmp_gt_i32_e64 s[4:5], 0, v5
	s_nop 1
	v_cndmask_b32_e64 v2, v7, v6, s[4:5]
	v_cmp_gt_u32_e64 s[4:5], v3, v0
	v_cmp_gt_u32_e64 s[6:7], v2, v94
	s_and_b64 s[10:11], s[0:1], s[4:5]
	s_and_b64 s[4:5], s[2:3], s[6:7]
	s_and_b64 s[2:3], s[10:11], exec
	s_and_b64 s[0:1], s[4:5], exec
	s_or_b64 s[6:7], s[0:1], s[2:3]
	s_cmp_eq_u64 s[6:7], 0
	s_cbranch_scc1 .LBB0_511
	s_and_saveexec_b64 s[6:7], s[10:11]
	s_cbranch_execz .LBB0_508
	v_mov_b32_e32 v4, s3
	v_mov_b32_e32 v5, s2
	v_cndmask_b32_e32 v4, v4, v5, vcc
	v_and_b32_e32 v4, v4, v218
	v_bcnt_u32_b32 v4, v4, 0
	v_cndmask_b32_e32 v5, v187, v173, vcc
	v_add3_u32 v4, v5, v214, v4
	v_lshl_add_u32 v5, v4, 2, v190
	ds_write_b32 v5, v3
	v_lshlrev_b32_e32 v3, 1, v4
	v_sub_u32_e32 v3, v5, v3
	ds_write_b16 v3, v78 offset:10240

; DI f32x16 mfma32(bf16x8 a, bf16x8 b, f32x16 c) { return __builtin_amdgcn_mfma_f32_32x32x16_bf16(a, b, c, 0, 0, 0); }
; DI u32 mono_key(float f) { u32 u = __float_as_uint(f); return (u & 0x80000000u) ? ~u : (u | 0x80000000u); }
; DI void dsa_item(const Params& p, int l, int tile32, int b, char* smem) {
;     ...
;       for (int t = 0; t < 4; ++t) {
;         const int key = (g * 4 + t) * 32 + c31;
;         f32x16 acc;
; #pragma unroll
;         for (int j = 0; j < 16; ++j) acc[j] = 0.f;
; #pragma unroll
;         for (int s = 0; s < 4; ++s) acc = mfma32(qa[s], kc[t][s], acc);
;         f32x2 ss2 = f32x2{0.f, 0.f};
; #pragma unroll
;         for (int hq = 0; hq < 8; ++hq) {
;           const f32x2 rr = f32x2{__builtin_amdgcn_fmed3f(acc[2 * hq], 0.f, 3.0e38f), __builtin_amdgcn_fmed3f(acc[2 * hq + 1], 0.f, 3.0e38f)};
;           ss2 = __builtin_elementwise_fma(wq2[hq], rr, ss2);
;         }
;         const float s0 = ss2.x, s1 = ss2.y;
;         const u32 k0 = mono_key(s0), k1 = mono_key(s1);
;         const bool c0 = (key <= qpos0) && (k0 > tauA), c1 = (key <= qpos0 + 1) && (k1 > tauB);
;         const u64 m0 = __ballot(c0), m1 = __ballot(c1);
;         if (m0 | m1) {
;           const u32 h0 = hh ? (u32)(m0 >> 32) : (u32)m0, h1 = hh ? (u32)(m1 >> 32) : (u32)m1;
;           const int pA = (hh ? cnt2 : cnt0) + __popc(h0 & lmask), pB = (hh ? cnt3 : cnt1) + __popc(h1 & lmask);
;           if (c0) { ckey[(2 * hh) * DCAP + pA] = k0; cidx[(2 * hh) * DCAP + pA] = (u16)key; }
;           if (c1) { ckey[(2 * hh + 1) * DCAP + pB] = k1; cidx[(2 * hh + 1) * DCAP + pB] = (u16)key; }
;           cnt0 += __popc((u32)m0); cnt2 += __popc((u32)(m0 >> 32));
;           cnt1 += __popc((u32)m1); cnt3 += __popc((u32)(m1 >> 32));
;         }
.LBB0_511:
	v_mfma_f32_32x32x16_bf16 v[2:17], v[18:21], v[70:73], 0
	v_mfma_f32_32x32x16_bf16 v[2:17], v[22:25], v[66:69], v[2:17]
	v_mfma_f32_32x32x16_bf16 v[2:17], v[26:29], v[62:65], v[2:17]
	v_or_b32_e32 v62, 64, v95
	v_cmp_le_i32_e64 s[0:1], v62, v217
	v_cmp_le_i32_e64 s[2:3], v62, v219
	v_mfma_f32_32x32x16_bf16 v[2:17], v[30:33], v[58:61], v[2:17]
	s_nop 11
	v_med3_f32 v2, v2, 0, v204
	v_med3_f32 v3, v3, 0, v204
	v_med3_f32 v4, v4, 0, v204
	v_med3_f32 v5, v5, 0, v204
	v_fma_f32 v2, v178, v2, 0
	v_fma_f32 v3, v179, v3, 0
	v_med3_f32 v6, v6, 0, v204
	v_med3_f32 v7, v7, 0, v204
	v_fmac_f32_e32 v2, v38, v4
	v_fmac_f32_e32 v3, v39, v5
	v_med3_f32 v8, v8, 0, v204
	v_med3_f32 v9, v9, 0, v204
	v_fmac_f32_e32 v2, v180, v6
	v_fmac_f32_e32 v3, v181, v7
	v_med3_f32 v10, v10, 0, v204
	v_med3_f32 v11, v11, 0, v204
	v_fmac_f32_e32 v2, v40, v8
	v_fmac_f32_e32 v3, v41, v9
	v_med3_f32 v12, v12, 0, v204
	v_med3_f32 v13, v13, 0, v204
	v_fmac_f32_e32 v2, v182, v10
	v_fmac_f32_e32 v3, v183, v11
	v_med3_f32 v14, v14, 0, v204
	v_med3_f32 v15, v15, 0, v204
	v_fmac_f32_e32 v2, v34, v12
	v_fmac_f32_e32 v3, v35, v13
	v_med3_f32 v16, v16, 0, v204
	v_med3_f32 v17, v17, 0, v204
	v_fmac_f32_e32 v2, v184, v14
	v_fmac_f32_e32 v3, v185, v15
	s_nop 0
	v_fma_f32 v4, v36, v16, v2
	v_fma_f32 v5, v37, v17, v3
	s_nop 0
	v_not_b32_e32 v2, v4
	v_or_b32_e32 v3, 0x80000000, v4
	v_cmp_gt_i32_e64 s[4:5], 0, v4
	v_not_b32_e32 v6, v5
	v_or_b32_e32 v7, 0x80000000, v5
	v_cndmask_b32_e64 v3, v3, v2, s[4:5]
	v_cmp_gt_i32_e64 s[4:5], 0, v5
	s_nop 1
	v_cndmask_b32_e64 v2, v7, v6, s[4:5]
	v_cmp_gt_u32_e64 s[4:5], v3, v0
	v_cmp_gt_u32_e64 s[6:7], v2, v94
	s_and_b64 s[10:11], s[0:1], s[4:5]
	s_and_b64 s[4:5], s[2:3], s[6:7]
	s_and_b64 s[2:3], s[10:11], exec
	s_and_b64 s[0:1], s[4:5], exec
	s_or_b64 s[6:7], s[0:1], s[2:3]
	s_cmp_eq_u64 s[6:7], 0
	s_cbranch_scc1 .LBB0_517
	s_and_saveexec_b64 s[6:7], s[10:11]
	s_cbranch_execz .LBB0_514
	v_mov_b32_e32 v4, s3
	v_mov_b32_e32 v5, s2
	v_cndmask_b32_e32 v4, v4, v5, vcc
	v_and_b32_e32 v4, v4, v218
	v_bcnt_u32_b32 v4, v4, 0
	v_cndmask_b32_e32 v5, v187, v173, vcc
	v_add3_u32 v4, v5, v214, v4
	v_lshl_add_u32 v5, v4, 2, v190
	ds_write_b32 v5, v3
	v_lshlrev_b32_e32 v3, 1, v4
	v_sub_u32_e32 v3, v5, v3
	ds_write_b16 v3, v62 offset:10240

; DI f32x16 mfma32(bf16x8 a, bf16x8 b, f32x16 c) { return __builtin_amdgcn_mfma_f32_32x32x16_bf16(a, b, c, 0, 0, 0); }
; DI u32 mono_key(float f) { u32 u = __float_as_uint(f); return (u & 0x80000000u) ? ~u : (u | 0x80000000u); }
; DI void dsa_item(const Params& p, int l, int tile32, int b, char* smem) {
;     ...
;       for (int t = 0; t < 4; ++t) {
;         const int key = (g * 4 + t) * 32 + c31;
;         f32x16 acc;
; #pragma unroll
;         for (int j = 0; j < 16; ++j) acc[j] = 0.f;
; #pragma unroll
;         for (int s = 0; s < 4; ++s) acc = mfma32(qa[s], kc[t][s], acc);
;         f32x2 ss2 = f32x2{0.f, 0.f};
; #pragma unroll
;         for (int hq = 0; hq < 8; ++hq) {
;           const f32x2 rr = f32x2{__builtin_amdgcn_fmed3f(acc[2 * hq], 0.f, 3.0e38f), __builtin_amdgcn_fmed3f(acc[2 * hq + 1], 0.f, 3.0e38f)};
;           ss2 = __builtin_elementwise_fma(wq2[hq], rr, ss2);
;         }
;         const float s0 = ss2.x, s1 = ss2.y;
;         const u32 k0 = mono_key(s0), k1 = mono_key(s1);
;         const bool c0 = (key <= qpos0) && (k0 > tauA), c1 = (key <= qpos0 + 1) && (k1 > tauB);
;         const u64 m0 = __ballot(c0), m1 = __ballot(c1);
;         if (m0 | m1) {
;           const u32 h0 = hh ? (u32)(m0 >> 32) : (u32)m0, h1 = hh ? (u32)(m1 >> 32) : (u32)m1;
;           const int pA = (hh ? cnt2 : cnt0) + __popc(h0 & lmask), pB = (hh ? cnt3 : cnt1) + __popc(h1 & lmask);
;           if (c0) { ckey[(2 * hh) * DCAP + pA] = k0; cidx[(2 * hh) * DCAP + pA] = (u16)key; }
;           if (c1) { ckey[(2 * hh + 1) * DCAP + pB] = k1; cidx[(2 * hh + 1) * DCAP + pB] = (u16)key; }
;           cnt0 += __popc((u32)m0); cnt2 += __popc((u32)(m0 >> 32));
;           cnt1 += __popc((u32)m1); cnt3 += __popc((u32)(m1 >> 32));
;         }
.LBB0_517:
	v_mfma_f32_32x32x16_bf16 v[2:17], v[18:21], v[54:57], 0
	v_mfma_f32_32x32x16_bf16 v[2:17], v[22:25], v[50:53], v[2:17]
	v_mfma_f32_32x32x16_bf16 v[2:17], v[26:29], v[46:49], v[2:17]
	v_or_b32_e32 v46, 0x60, v95
	v_cmp_le_i32_e64 s[0:1], v46, v217
	v_cmp_le_i32_e64 s[2:3], v46, v219
	v_mfma_f32_32x32x16_bf16 v[2:17], v[30:33], v[42:45], v[2:17]
	s_nop 11
	v_med3_f32 v2, v2, 0, v204
	v_med3_f32 v3, v3, 0, v204
	v_med3_f32 v4, v4, 0, v204
	v_med3_f32 v5, v5, 0, v204
	v_fma_f32 v2, v178, v2, 0
	v_fma_f32 v3, v179, v3, 0
	v_med3_f32 v6, v6, 0, v204
	v_med3_f32 v7, v7, 0, v204
	v_fmac_f32_e32 v2, v38, v4
	v_fmac_f32_e32 v3, v39, v5
	v_med3_f32 v8, v8, 0, v204
	v_med3_f32 v9, v9, 0, v204
	v_fmac_f32_e32 v2, v180, v6
	v_fmac_f32_e32 v3, v181, v7
	v_med3_f32 v10, v10, 0, v204
	v_med3_f32 v11, v11, 0, v204
	v_fmac_f32_e32 v2, v40, v8
	v_fmac_f32_e32 v3, v41, v9
	v_med3_f32 v12, v12, 0, v204
	v_med3_f32 v13, v13, 0, v204
	v_fmac_f32_e32 v2, v182, v10
	v_fmac_f32_e32 v3, v183, v11
	v_med3_f32 v14, v14, 0, v204
	v_med3_f32 v15, v15, 0, v204
	v_fmac_f32_e32 v2, v34, v12
	v_fmac_f32_e32 v3, v35, v13
	v_med3_f32 v16, v16, 0, v204
	v_med3_f32 v17, v17, 0, v204
	v_fmac_f32_e32 v2, v184, v14
	v_fmac_f32_e32 v3, v185, v15
	s_nop 0
	v_fma_f32 v4, v36, v16, v2
	v_fma_f32 v5, v37, v17, v3
	s_nop 0
	v_not_b32_e32 v2, v4
	v_or_b32_e32 v3, 0x80000000, v4
	v_cmp_gt_i32_e64 s[4:5], 0, v4
	v_not_b32_e32 v6, v5
	v_or_b32_e32 v7, 0x80000000, v5
	v_cndmask_b32_e64 v3, v3, v2, s[4:5]
	v_cmp_gt_i32_e64 s[4:5], 0, v5
	s_nop 1
	v_cndmask_b32_e64 v2, v7, v6, s[4:5]
	v_cmp_gt_u32_e64 s[4:5], v3, v0
	v_cmp_gt_u32_e64 s[6:7], v2, v94
	s_and_b64 s[10:11], s[0:1], s[4:5]
	s_and_b64 s[4:5], s[2:3], s[6:7]
	s_and_b64 s[2:3], s[10:11], exec
	s_and_b64 s[0:1], s[4:5], exec
	s_or_b64 s[6:7], s[0:1], s[2:3]
	s_cmp_eq_u64 s[6:7], 0
	s_cbranch_scc1 .LBB0_374
	s_and_saveexec_b64 s[6:7], s[10:11]
	s_cbranch_execz .LBB0_520
	v_mov_b32_e32 v0, s3
	v_mov_b32_e32 v4, s2
	v_cndmask_b32_e32 v0, v0, v4, vcc
	v_and_b32_e32 v0, v0, v218
	v_bcnt_u32_b32 v0, v0, 0
	v_cndmask_b32_e32 v4, v187, v173, vcc
	v_add3_u32 v0, v4, v214, v0
	v_lshl_add_u32 v4, v0, 2, v190
	v_lshlrev_b32_e32 v0, 1, v0
	v_sub_u32_e32 v0, v4, v0
	ds_write_b32 v4, v3
	ds_write_b16 v0, v46 offset:10240
